# speedup vs baseline: 1.0250x; 1.0144x over previous
;     __device__ __forceinline__ void fused(f32x4 (&acc)[2][2][4][2], const Unit& u, int wr, int wc, int fr, int fq, LAS unsigned char* lds) const {
;     ...
;         const int rl0 = wr * 64 + fr, col0 = u.pn * BM + wc * 32 + 4 * fq;
; #pragma unroll
;         for (int ai = 0; ai < 2; ++ai)
; #pragma unroll
;             for (int m = 0; m < 4; ++m) { const int rl = rl0 + ai * HALF + m * 16; const size_t roff = (size_t)(u.pm * BM + rl) * LDX + col0; float s = 0.f, q = 0.f;
; #pragma unroll
;                 for (int bj = 0; bj < 2; ++bj)
; #pragma unroll
;                     for (int n = 0; n < 2; ++n) { const u32x2 w = *(const u32x2*)(res + roff + bj * HALF + n * 16); f32x4 o = acc[ai][bj][m][n];
;                         o[0] += ALPHA * __uint_as_float(w.x << 16); o[1] += ALPHA * __uint_as_float(w.x & 0xffff0000u); o[2] += ALPHA * __uint_as_float(w.y << 16); o[3] += ALPHA * __uint_as_float(w.y & 0xffff0000u);
;                         acc[ai][bj][m][n] = o; s += (o[0] + o[1]) + (o[2] + o[3]); q += (o[0] * o[0] + o[1] * o[1]) + (o[2] * o[2] + o[3] * o[3]); }
;                 s += __shfl_xor(s, 16); s += __shfl_xor(s, 32); q += __shfl_xor(q, 16); q += __shfl_xor(q, 32);
;                 if (fq == 0) { P[(rl * 4 + wc) * 2] = s; P[(rl * 4 + wc) * 2 + 1] = q; }
.LBB0_551:
	s_lshl_b32 s2, s88, 8
	v_add_u32_e32 v138, s2, v219
	v_mov_b64_e32 v[136:137], s[28:29]
	v_ashrrev_i32_e32 v135, 31, v134
	v_mad_i64_i32 v[136:137], s[0:1], v138, s93, v[136:137]
	v_mov_b32_e32 v246, v200
	v_lshl_add_u64 v[140:141], v[134:135], 1, v[136:137]
	v_lshl_add_u64 v[198:199], v[134:135], 1, s[28:29]
	v_add_u32_e32 v188, s2, v219
	v_mad_i64_i32 v[188:189], s[0:1], v188, s93, v[198:199]
	global_load_dwordx2 v[188:189], v[188:189], off
	v_add_u32_e32 v190, s2, v219
	v_mad_i64_i32 v[190:191], s[0:1], v190, s93, v[198:199]
	global_load_dwordx2 v[190:191], v[190:191], off offset:32
	v_add_u32_e32 v192, s2, v219
	v_mad_i64_i32 v[192:193], s[0:1], v192, s93, v[198:199]
	global_load_dwordx2 v[192:193], v[192:193], off offset:256
	v_add_u32_e32 v194, s2, v219
	v_mad_i64_i32 v[194:195], s[0:1], v194, s93, v[198:199]
	global_load_dwordx2 v[194:195], v[194:195], off offset:288
	v_add_u32_e32 v196, s2, v221
	v_mad_i64_i32 v[196:197], s[0:1], v196, s93, v[198:199]
	global_load_dwordx2 v[196:197], v[196:197], off
	v_add_u32_e32 v208, s2, v221
	v_mad_i64_i32 v[208:209], s[0:1], v208, s93, v[198:199]
	global_load_dwordx2 v[208:209], v[208:209], off offset:32
	v_add_u32_e32 v210, s2, v221
	v_mad_i64_i32 v[210:211], s[0:1], v210, s93, v[198:199]
	global_load_dwordx2 v[210:211], v[210:211], off offset:256
	v_add_u32_e32 v212, s2, v221
	v_mad_i64_i32 v[212:213], s[0:1], v212, s93, v[198:199]
	global_load_dwordx2 v[212:213], v[212:213], off offset:288
	v_cmp_lt_i32_e32 vcc, v206, v204
	s_waitcnt vmcnt(7)
	v_mov_b32_e32 v136, v188
	v_mov_b32_e32 v137, v189
	v_add_u32_e32 v188, s2, v222
	v_mad_i64_i32 v[188:189], s[0:1], v188, s93, v[198:199]
	global_load_dwordx2 v[188:189], v[188:189], off
	v_lshlrev_b32_e32 v156, 16, v136
	v_and_b32_e32 v158, 0xffff0000, v136
	v_lshlrev_b32_e32 v154, 16, v137
	v_and_b32_e32 v152, 0xffff0000, v137
	v_cndmask_b32_e32 v64, v203, v206, vcc
	v_lshlrev_b32_e32 v139, 2, v64
	v_cmp_lt_i32_e32 vcc, v205, v204
	s_waitcnt vmcnt(7)
	v_mov_b32_e32 v136, v190
	v_mov_b32_e32 v137, v191
	v_add_u32_e32 v190, s2, v222
	v_mad_i64_i32 v[190:191], s[0:1], v190, s93, v[198:199]
	global_load_dwordx2 v[190:191], v[190:191], off offset:32
	v_lshlrev_b32_e32 v157, 16, v136
	v_and_b32_e32 v155, 0xffff0000, v136
	v_lshlrev_b32_e32 v136, 16, v137
	v_and_b32_e32 v137, 0xffff0000, v137
	v_pk_fma_f32 v[136:137], v[136:137], s[30:31], v[116:117] op_sel_hi:[1,0,1]
	v_mov_b32_e32 v159, v157
	v_mul_f32_e32 v116, v136, v136
	v_pk_fma_f32 v[150:151], v[136:137], v[136:137], v[116:117] op_sel_hi:[1,1,0]
	v_mov_b32_e32 v153, v155
	v_mov_b32_e32 v150, v65
	v_cndmask_b32_e32 v64, v203, v205, vcc
	v_lshlrev_b32_e32 v64, 2, v64
	s_waitcnt vmcnt(6)
	v_mov_b32_e32 v116, v192
	v_mov_b32_e32 v117, v193
	v_mov_b32_e32 v140, v194
	v_mov_b32_e32 v141, v195
	v_add_u32_e32 v192, s2, v222
	v_mad_i64_i32 v[192:193], s[0:1], v192, s93, v[198:199]
	global_load_dwordx2 v[192:193], v[192:193], off offset:256
	v_add_u32_e32 v194, s2, v222
	v_mad_i64_i32 v[194:195], s[0:1], v194, s93, v[198:199]
	global_load_dwordx2 v[194:195], v[194:195], off offset:288
	v_lshlrev_b32_e32 v142, 16, v116
	v_and_b32_e32 v143, 0xffff0000, v116
	v_lshlrev_b32_e32 v116, 16, v117
	v_and_b32_e32 v117, 0xffff0000, v117
	v_pk_fma_f32 v[128:129], v[116:117], s[30:31], v[128:129] op_sel_hi:[1,0,1]
	v_lshlrev_b32_e32 v116, 16, v140
	v_and_b32_e32 v117, 0xffff0000, v140
	v_pk_fma_f32 v[116:117], v[116:117], s[30:31], v[122:123] op_sel_hi:[1,0,1]
	v_lshlrev_b32_e32 v122, 16, v141
	v_and_b32_e32 v123, 0xffff0000, v141
	v_pk_fma_f32 v[122:123], v[122:123], s[30:31], v[124:125] op_sel_hi:[1,0,1]
	v_mov_b32_e32 v124, v118
	v_mov_b32_e32 v125, v114
	v_pk_mov_b32 v[118:119], v[118:119], v[114:115] op_sel:[1,0]
	v_mov_b32_e32 v114, v120
	v_pk_fma_f32 v[124:125], v[156:157], s[30:31], v[124:125] op_sel_hi:[1,0,1]
	v_pk_fma_f32 v[140:141], v[158:159], s[30:31], v[118:119] op_sel_hi:[1,0,1]
	v_pk_fma_f32 v[118:119], v[154:155], s[30:31], v[114:115] op_sel_hi:[1,0,1]
	v_mov_b32_e32 v114, v121
	v_pk_fma_f32 v[120:121], v[152:153], s[30:31], v[114:115] op_sel_hi:[1,0,1]
	v_pk_mul_f32 v[114:115], v[124:125], v[124:125]
	v_pk_mul_f32 v[152:153], v[140:141], v[140:141]
	v_pk_mul_f32 v[154:155], v[118:119], v[118:119]
	v_pk_mul_f32 v[156:157], v[120:121], v[120:121]
	v_pk_mov_b32 v[114:115], v[124:125], v[114:115] op_sel:[1,0]
	v_pk_mov_b32 v[152:153], v[118:119], v[152:153] op_sel:[1,0]
	v_pk_fma_f32 v[126:127], v[142:143], s[30:31], v[126:127] op_sel_hi:[1,0,1]
	v_pk_add_f32 v[114:115], v[114:115], v[152:153]
	v_mov_b32_e32 v152, v136
	v_mov_b32_e32 v153, v154
	v_pk_mov_b32 v[154:155], v[136:137], v[156:157] op_sel:[1,0]
	v_pk_mul_f32 v[156:157], v[118:119], v[120:121]
	v_pk_add_f32 v[152:153], v[152:153], v[154:155]
	v_pk_mul_f32 v[154:155], v[124:125], v[140:141]
	v_pk_add_f32 v[114:115], v[114:115], v[152:153]
	v_pk_add_f32 v[152:153], v[124:125], v[140:141]
	v_pk_mul_f32 v[148:149], v[126:127], v[126:127]
	v_mov_b32_e32 v153, v155
	v_pk_add_f32 v[154:155], v[118:119], v[120:121]
	v_pk_mul_f32 v[144:145], v[128:129], v[128:129]
	v_mov_b32_e32 v155, v157
	v_pk_add_f32 v[152:153], v[152:153], v[154:155]
	v_pk_mul_f32 v[146:147], v[116:117], v[116:117]
	v_pk_add_f32 v[150:151], v[152:153], v[150:151]
	v_pk_mul_f32 v[142:143], v[122:123], v[122:123]
	v_pk_add_f32 v[114:115], v[114:115], v[150:151]
	v_mov_b32_e32 v150, v126
	v_mov_b32_e32 v151, v148
	v_mov_b32_e32 v148, v127
	v_pk_add_f32 v[148:149], v[150:151], v[148:149]
	v_mov_b32_e32 v150, v128
	v_mov_b32_e32 v151, v144
	v_mov_b32_e32 v144, v129
	v_pk_add_f32 v[144:145], v[150:151], v[144:145]
	s_nop 0
	v_pk_add_f32 v[144:145], v[148:149], v[144:145]
	s_nop 0
	v_pk_add_f32 v[114:115], v[114:115], v[144:145]
	v_mov_b32_e32 v144, v116
	v_mov_b32_e32 v145, v146
	v_mov_b32_e32 v146, v117
	v_pk_add_f32 v[144:145], v[144:145], v[146:147]
	v_mov_b32_e32 v146, v122
	v_mov_b32_e32 v147, v142
	v_mov_b32_e32 v142, v123
	v_pk_add_f32 v[142:143], v[146:147], v[142:143]
	s_nop 0
	v_pk_add_f32 v[142:143], v[144:145], v[142:143]
	s_nop 0
	v_pk_add_f32 v[114:115], v[114:115], v[142:143]
	ds_bpermute_b32 v142, v139, v114
	ds_bpermute_b32 v143, v139, v115
	s_waitcnt lgkmcnt(0)
	v_pk_add_f32 v[114:115], v[114:115], v[142:143]
	ds_bpermute_b32 v142, v64, v114
	ds_bpermute_b32 v143, v64, v115
	s_and_saveexec_b64 s[0:1], s[40:41]
	s_cbranch_execz .LBB0_553
	s_waitcnt lgkmcnt(0)
	v_pk_add_f32 v[114:115], v[114:115], v[142:143]
	ds_write_b64 v230, v[114:115]
;     __device__ __forceinline__ void fused(f32x4 (&acc)[2][2][4][2], const Unit& u, int wr, int wc, int fr, int fq, LAS unsigned char* lds) const {
;     ...
;             for (int m = 0; m < 4; ++m) { const int rl = rl0 + ai * HALF + m * 16; const size_t roff = (size_t)(u.pm * BM + rl) * LDX + col0; float s = 0.f, q = 0.f;
; #pragma unroll
;                 for (int bj = 0; bj < 2; ++bj)
; #pragma unroll
;                     for (int n = 0; n < 2; ++n) { const u32x2 w = *(const u32x2*)(res + roff + bj * HALF + n * 16); f32x4 o = acc[ai][bj][m][n];
;                         o[0] += ALPHA * __uint_as_float(w.x << 16); o[1] += ALPHA * __uint_as_float(w.x & 0xffff0000u); o[2] += ALPHA * __uint_as_float(w.y << 16); o[3] += ALPHA * __uint_as_float(w.y & 0xffff0000u);
;                         acc[ai][bj][m][n] = o; s += (o[0] + o[1]) + (o[2] + o[3]); q += (o[0] * o[0] + o[1] * o[1]) + (o[2] * o[2] + o[3] * o[3]); }
;                 s += __shfl_xor(s, 16); s += __shfl_xor(s, 32); q += __shfl_xor(q, 16); q += __shfl_xor(q, 32);
;                 if (fq == 0) { P[(rl * 4 + wc) * 2] = s; P[(rl * 4 + wc) * 2 + 1] = q; }
;                 asm volatile("" ::: "memory"); }
.LBB0_553:
	s_or_b64 exec, exec, s[0:1]
	s_waitcnt lgkmcnt(1)
	v_add_u32_e32 v142, s2, v221
	v_mov_b64_e32 v[114:115], s[28:29]
	v_mad_i64_i32 v[114:115], s[0:1], v142, s93, v[114:115]
	v_lshl_add_u64 v[144:145], v[134:135], 1, v[114:115]
	s_waitcnt vmcnt(7)
	v_mov_b32_e32 v114, v196
	v_mov_b32_e32 v115, v197
	v_add_u32_e32 v196, s2, v223
	v_mad_i64_i32 v[196:197], s[0:1], v196, s93, v[198:199]
	global_load_dwordx2 v[196:197], v[196:197], off
	v_lshlrev_b32_e32 v160, 16, v114
	v_and_b32_e32 v162, 0xffff0000, v114
	v_lshlrev_b32_e32 v158, 16, v115
	v_and_b32_e32 v156, 0xffff0000, v115
	s_waitcnt vmcnt(7)
	v_mov_b32_e32 v114, v208
	v_mov_b32_e32 v115, v209
	v_add_u32_e32 v208, s2, v223
	v_mad_i64_i32 v[208:209], s[0:1], v208, s93, v[198:199]
	global_load_dwordx2 v[208:209], v[208:209], off offset:32
	v_lshlrev_b32_e32 v161, 16, v114
	v_and_b32_e32 v159, 0xffff0000, v114
	v_lshlrev_b32_e32 v114, 16, v115
	v_and_b32_e32 v115, 0xffff0000, v115
	v_pk_fma_f32 v[114:115], v[114:115], s[30:31], v[100:101] op_sel_hi:[1,0,1]
	v_mov_b32_e32 v163, v161
	v_mul_f32_e32 v100, v114, v114
	v_pk_fma_f32 v[154:155], v[114:115], v[114:115], v[100:101] op_sel_hi:[1,1,0]
	v_mov_b32_e32 v157, v159
	v_mov_b32_e32 v154, v65
	s_waitcnt vmcnt(7)
	v_mov_b32_e32 v100, v210
	v_mov_b32_e32 v101, v211
	v_add_u32_e32 v210, s2, v223
	v_mad_i64_i32 v[210:211], s[0:1], v210, s93, v[198:199]
	global_load_dwordx2 v[210:211], v[210:211], off offset:256
	v_lshlrev_b32_e32 v146, 16, v100
	v_and_b32_e32 v147, 0xffff0000, v100
	v_lshlrev_b32_e32 v100, 16, v101
	v_and_b32_e32 v101, 0xffff0000, v101
	v_pk_fma_f32 v[112:113], v[100:101], s[30:31], v[112:113] op_sel_hi:[1,0,1]
	s_waitcnt vmcnt(7)
	v_mov_b32_e32 v144, v212
	v_mov_b32_e32 v145, v213
	v_add_u32_e32 v212, s2, v223
	v_mad_i64_i32 v[212:213], s[0:1], v212, s93, v[198:199]
	global_load_dwordx2 v[212:213], v[212:213], off offset:288
	v_lshlrev_b32_e32 v100, 16, v144
	v_and_b32_e32 v101, 0xffff0000, v144
	v_pk_fma_f32 v[100:101], v[100:101], s[30:31], v[106:107] op_sel_hi:[1,0,1]
	v_lshlrev_b32_e32 v106, 16, v145
	v_and_b32_e32 v107, 0xffff0000, v145
	v_pk_fma_f32 v[106:107], v[106:107], s[30:31], v[108:109] op_sel_hi:[1,0,1]
	v_mov_b32_e32 v108, v102
	v_mov_b32_e32 v109, v98
	v_pk_mov_b32 v[102:103], v[102:103], v[98:99] op_sel:[1,0]
	v_mov_b32_e32 v98, v104
	v_pk_fma_f32 v[108:109], v[160:161], s[30:31], v[108:109] op_sel_hi:[1,0,1]
	v_pk_fma_f32 v[144:145], v[162:163], s[30:31], v[102:103] op_sel_hi:[1,0,1]
	v_pk_fma_f32 v[102:103], v[158:159], s[30:31], v[98:99] op_sel_hi:[1,0,1]
	v_mov_b32_e32 v98, v105
	v_pk_fma_f32 v[104:105], v[156:157], s[30:31], v[98:99] op_sel_hi:[1,0,1]
	v_pk_mul_f32 v[98:99], v[108:109], v[108:109]
	v_pk_mul_f32 v[156:157], v[144:145], v[144:145]
	v_pk_mul_f32 v[158:159], v[102:103], v[102:103]
	v_pk_mul_f32 v[160:161], v[104:105], v[104:105]
	v_pk_mov_b32 v[98:99], v[108:109], v[98:99] op_sel:[1,0]
	v_pk_mov_b32 v[156:157], v[102:103], v[156:157] op_sel:[1,0]
	v_pk_fma_f32 v[110:111], v[146:147], s[30:31], v[110:111] op_sel_hi:[1,0,1]
	v_pk_add_f32 v[98:99], v[98:99], v[156:157]
	v_mov_b32_e32 v156, v114
	v_mov_b32_e32 v157, v158
	v_pk_mov_b32 v[158:159], v[114:115], v[160:161] op_sel:[1,0]
	v_pk_mul_f32 v[160:161], v[102:103], v[104:105]
	v_pk_add_f32 v[156:157], v[156:157], v[158:159]
	v_pk_mul_f32 v[158:159], v[108:109], v[144:145]
	v_pk_add_f32 v[98:99], v[98:99], v[156:157]
	v_pk_add_f32 v[156:157], v[108:109], v[144:145]
	v_pk_mul_f32 v[152:153], v[110:111], v[110:111]
	v_mov_b32_e32 v157, v159
	v_pk_add_f32 v[158:159], v[102:103], v[104:105]
	v_pk_mul_f32 v[148:149], v[112:113], v[112:113]
	v_mov_b32_e32 v159, v161
	v_pk_add_f32 v[156:157], v[156:157], v[158:159]
	v_pk_mul_f32 v[150:151], v[100:101], v[100:101]
	v_pk_add_f32 v[154:155], v[156:157], v[154:155]
	v_pk_mul_f32 v[146:147], v[106:107], v[106:107]
	v_pk_add_f32 v[98:99], v[98:99], v[154:155]
	v_mov_b32_e32 v154, v110
	v_mov_b32_e32 v155, v152
	v_mov_b32_e32 v152, v111
	v_pk_add_f32 v[152:153], v[154:155], v[152:153]
	v_mov_b32_e32 v154, v112
	v_mov_b32_e32 v155, v148
	v_mov_b32_e32 v148, v113
	v_pk_add_f32 v[148:149], v[154:155], v[148:149]
	s_nop 0
	v_pk_add_f32 v[148:149], v[152:153], v[148:149]
	s_nop 0
	v_pk_add_f32 v[98:99], v[98:99], v[148:149]
	v_mov_b32_e32 v148, v100
	v_mov_b32_e32 v149, v150
	v_mov_b32_e32 v150, v101
	v_pk_add_f32 v[148:149], v[148:149], v[150:151]
	v_mov_b32_e32 v150, v106
	v_mov_b32_e32 v151, v146
	v_mov_b32_e32 v146, v107
	v_pk_add_f32 v[146:147], v[150:151], v[146:147]
	s_nop 0
	v_pk_add_f32 v[146:147], v[148:149], v[146:147]
	s_nop 0
	v_pk_add_f32 v[98:99], v[98:99], v[146:147]
	ds_bpermute_b32 v146, v139, v98
	ds_bpermute_b32 v147, v139, v99
	s_waitcnt lgkmcnt(0)
	v_pk_add_f32 v[98:99], v[98:99], v[146:147]
	ds_bpermute_b32 v146, v64, v98
	ds_bpermute_b32 v147, v64, v99
	s_and_saveexec_b64 s[0:1], s[40:41]
	s_cbranch_execz .LBB0_555
	s_waitcnt lgkmcnt(0)
	v_pk_add_f32 v[98:99], v[98:99], v[146:147]
	ds_write_b64 v231, v[98:99]
;     __device__ __forceinline__ void fused(f32x4 (&acc)[2][2][4][2], const Unit& u, int wr, int wc, int fr, int fq, LAS unsigned char* lds) const {
;     ...
;             for (int m = 0; m < 4; ++m) { const int rl = rl0 + ai * HALF + m * 16; const size_t roff = (size_t)(u.pm * BM + rl) * LDX + col0; float s = 0.f, q = 0.f;
; #pragma unroll
;                 for (int bj = 0; bj < 2; ++bj)
; #pragma unroll
;                     for (int n = 0; n < 2; ++n) { const u32x2 w = *(const u32x2*)(res + roff + bj * HALF + n * 16); f32x4 o = acc[ai][bj][m][n];
;                         o[0] += ALPHA * __uint_as_float(w.x << 16); o[1] += ALPHA * __uint_as_float(w.x & 0xffff0000u); o[2] += ALPHA * __uint_as_float(w.y << 16); o[3] += ALPHA * __uint_as_float(w.y & 0xffff0000u);
;                         acc[ai][bj][m][n] = o; s += (o[0] + o[1]) + (o[2] + o[3]); q += (o[0] * o[0] + o[1] * o[1]) + (o[2] * o[2] + o[3] * o[3]); }
;                 s += __shfl_xor(s, 16); s += __shfl_xor(s, 32); q += __shfl_xor(q, 16); q += __shfl_xor(q, 32);
;                 if (fq == 0) { P[(rl * 4 + wc) * 2] = s; P[(rl * 4 + wc) * 2 + 1] = q; }
;                 asm volatile("" ::: "memory"); }
.LBB0_555:
	s_or_b64 exec, exec, s[0:1]
	s_waitcnt lgkmcnt(1)
	v_add_u32_e32 v146, s2, v222
	v_mov_b64_e32 v[98:99], s[28:29]
	v_mad_i64_i32 v[98:99], s[0:1], v146, s93, v[98:99]
	v_lshl_add_u64 v[148:149], v[134:135], 1, v[98:99]
	s_waitcnt vmcnt(7)
	v_mov_b32_e32 v98, v188
	v_mov_b32_e32 v99, v189
	v_add_u32_e32 v188, s2, v224
	v_mad_i64_i32 v[188:189], s[0:1], v188, s93, v[198:199]
	global_load_dwordx2 v[188:189], v[188:189], off
	v_lshlrev_b32_e32 v164, 16, v98
	v_and_b32_e32 v166, 0xffff0000, v98
	v_lshlrev_b32_e32 v162, 16, v99
	v_and_b32_e32 v160, 0xffff0000, v99
	s_waitcnt vmcnt(7)
	v_mov_b32_e32 v98, v190
	v_mov_b32_e32 v99, v191
	v_add_u32_e32 v190, s2, v224
	v_mad_i64_i32 v[190:191], s[0:1], v190, s93, v[198:199]
	global_load_dwordx2 v[190:191], v[190:191], off offset:32
	v_lshlrev_b32_e32 v165, 16, v98
	v_and_b32_e32 v163, 0xffff0000, v98
	v_lshlrev_b32_e32 v98, 16, v99
	v_and_b32_e32 v99, 0xffff0000, v99
	v_pk_fma_f32 v[98:99], v[98:99], s[30:31], v[84:85] op_sel_hi:[1,0,1]
	v_mov_b32_e32 v167, v165
	v_mul_f32_e32 v84, v98, v98
	v_pk_fma_f32 v[158:159], v[98:99], v[98:99], v[84:85] op_sel_hi:[1,1,0]
	v_mov_b32_e32 v161, v163
	v_mov_b32_e32 v158, v65
	s_waitcnt vmcnt(7)
	v_mov_b32_e32 v84, v192
	v_mov_b32_e32 v85, v193
	v_add_u32_e32 v192, s2, v224
	v_mad_i64_i32 v[192:193], s[0:1], v192, s93, v[198:199]
	global_load_dwordx2 v[192:193], v[192:193], off offset:256
	v_lshlrev_b32_e32 v150, 16, v84
	v_and_b32_e32 v151, 0xffff0000, v84
	v_lshlrev_b32_e32 v84, 16, v85
	v_and_b32_e32 v85, 0xffff0000, v85
	v_pk_fma_f32 v[96:97], v[84:85], s[30:31], v[96:97] op_sel_hi:[1,0,1]
	s_waitcnt vmcnt(7)
	v_mov_b32_e32 v148, v194
	v_mov_b32_e32 v149, v195
	v_add_u32_e32 v194, s2, v224
	v_mad_i64_i32 v[194:195], s[0:1], v194, s93, v[198:199]
	global_load_dwordx2 v[194:195], v[194:195], off offset:288
	v_lshlrev_b32_e32 v84, 16, v148
	v_and_b32_e32 v85, 0xffff0000, v148
	v_pk_fma_f32 v[84:85], v[84:85], s[30:31], v[90:91] op_sel_hi:[1,0,1]
	v_lshlrev_b32_e32 v90, 16, v149
	v_and_b32_e32 v91, 0xffff0000, v149
	v_pk_fma_f32 v[90:91], v[90:91], s[30:31], v[92:93] op_sel_hi:[1,0,1]
	v_mov_b32_e32 v92, v86
	v_mov_b32_e32 v93, v82
	v_pk_mov_b32 v[86:87], v[86:87], v[82:83] op_sel:[1,0]
	v_mov_b32_e32 v82, v88
	v_pk_fma_f32 v[92:93], v[164:165], s[30:31], v[92:93] op_sel_hi:[1,0,1]
	v_pk_fma_f32 v[148:149], v[166:167], s[30:31], v[86:87] op_sel_hi:[1,0,1]
	v_pk_fma_f32 v[86:87], v[162:163], s[30:31], v[82:83] op_sel_hi:[1,0,1]
	v_mov_b32_e32 v82, v89
	v_pk_fma_f32 v[88:89], v[160:161], s[30:31], v[82:83] op_sel_hi:[1,0,1]
	v_pk_mul_f32 v[82:83], v[92:93], v[92:93]
	v_pk_mul_f32 v[160:161], v[148:149], v[148:149]
	v_pk_mul_f32 v[162:163], v[86:87], v[86:87]
	v_pk_mul_f32 v[164:165], v[88:89], v[88:89]
	v_pk_mov_b32 v[82:83], v[92:93], v[82:83] op_sel:[1,0]
	v_pk_mov_b32 v[160:161], v[86:87], v[160:161] op_sel:[1,0]
	v_pk_fma_f32 v[94:95], v[150:151], s[30:31], v[94:95] op_sel_hi:[1,0,1]
	v_pk_add_f32 v[82:83], v[82:83], v[160:161]
	v_mov_b32_e32 v160, v98
	v_mov_b32_e32 v161, v162
	v_pk_mov_b32 v[162:163], v[98:99], v[164:165] op_sel:[1,0]
	v_pk_mul_f32 v[164:165], v[86:87], v[88:89]
	v_pk_add_f32 v[160:161], v[160:161], v[162:163]
	v_pk_mul_f32 v[162:163], v[92:93], v[148:149]
	v_pk_add_f32 v[82:83], v[82:83], v[160:161]
	v_pk_add_f32 v[160:161], v[92:93], v[148:149]
	v_pk_mul_f32 v[156:157], v[94:95], v[94:95]
	v_mov_b32_e32 v161, v163
	v_pk_add_f32 v[162:163], v[86:87], v[88:89]
	v_pk_mul_f32 v[152:153], v[96:97], v[96:97]
	v_mov_b32_e32 v163, v165
	v_pk_add_f32 v[160:161], v[160:161], v[162:163]
	v_pk_mul_f32 v[154:155], v[84:85], v[84:85]
	v_pk_add_f32 v[158:159], v[160:161], v[158:159]
	v_pk_mul_f32 v[150:151], v[90:91], v[90:91]
	v_pk_add_f32 v[82:83], v[82:83], v[158:159]
	v_mov_b32_e32 v158, v94
	v_mov_b32_e32 v159, v156
	v_mov_b32_e32 v156, v95
	v_pk_add_f32 v[156:157], v[158:159], v[156:157]
	v_mov_b32_e32 v158, v96
	v_mov_b32_e32 v159, v152
	v_mov_b32_e32 v152, v97
	v_pk_add_f32 v[152:153], v[158:159], v[152:153]
	s_nop 0
	v_pk_add_f32 v[152:153], v[156:157], v[152:153]
	s_nop 0
	v_pk_add_f32 v[82:83], v[82:83], v[152:153]
	v_mov_b32_e32 v152, v84
	v_mov_b32_e32 v153, v154
	v_mov_b32_e32 v154, v85
	v_pk_add_f32 v[152:153], v[152:153], v[154:155]
	v_mov_b32_e32 v154, v90
	v_mov_b32_e32 v155, v150
	v_mov_b32_e32 v150, v91
	v_pk_add_f32 v[150:151], v[154:155], v[150:151]
	s_nop 0
	v_pk_add_f32 v[150:151], v[152:153], v[150:151]
	s_nop 0
	v_pk_add_f32 v[82:83], v[82:83], v[150:151]
	ds_bpermute_b32 v150, v139, v82
	ds_bpermute_b32 v151, v139, v83
	s_waitcnt lgkmcnt(0)
	v_pk_add_f32 v[82:83], v[82:83], v[150:151]
	ds_bpermute_b32 v150, v64, v82
	ds_bpermute_b32 v151, v64, v83
	s_and_saveexec_b64 s[0:1], s[40:41]
	s_cbranch_execz .LBB0_557
	s_waitcnt lgkmcnt(0)
	v_pk_add_f32 v[82:83], v[82:83], v[150:151]
	ds_write_b64 v232, v[82:83]
;     __device__ __forceinline__ void fused(f32x4 (&acc)[2][2][4][2], const Unit& u, int wr, int wc, int fr, int fq, LAS unsigned char* lds) const {
;     ...
;             for (int m = 0; m < 4; ++m) { const int rl = rl0 + ai * HALF + m * 16; const size_t roff = (size_t)(u.pm * BM + rl) * LDX + col0; float s = 0.f, q = 0.f;
; #pragma unroll
;                 for (int bj = 0; bj < 2; ++bj)
; #pragma unroll
;                     for (int n = 0; n < 2; ++n) { const u32x2 w = *(const u32x2*)(res + roff + bj * HALF + n * 16); f32x4 o = acc[ai][bj][m][n];
;                         o[0] += ALPHA * __uint_as_float(w.x << 16); o[1] += ALPHA * __uint_as_float(w.x & 0xffff0000u); o[2] += ALPHA * __uint_as_float(w.y << 16); o[3] += ALPHA * __uint_as_float(w.y & 0xffff0000u);
;                         acc[ai][bj][m][n] = o; s += (o[0] + o[1]) + (o[2] + o[3]); q += (o[0] * o[0] + o[1] * o[1]) + (o[2] * o[2] + o[3] * o[3]); }
;                 s += __shfl_xor(s, 16); s += __shfl_xor(s, 32); q += __shfl_xor(q, 16); q += __shfl_xor(q, 32);
;                 if (fq == 0) { P[(rl * 4 + wc) * 2] = s; P[(rl * 4 + wc) * 2 + 1] = q; }
;                 asm volatile("" ::: "memory"); }
.LBB0_557:
	s_or_b64 exec, exec, s[0:1]
	s_waitcnt lgkmcnt(1)
	v_add_u32_e32 v150, s2, v223
	v_mov_b64_e32 v[82:83], s[28:29]
	v_mad_i64_i32 v[82:83], s[0:1], v150, s93, v[82:83]
	v_lshl_add_u64 v[152:153], v[134:135], 1, v[82:83]
	s_waitcnt vmcnt(7)
	v_mov_b32_e32 v82, v196
	v_mov_b32_e32 v83, v197
	v_add_u32_e32 v196, s2, v225
	v_mad_i64_i32 v[196:197], s[0:1], v196, s93, v[198:199]
	global_load_dwordx2 v[196:197], v[196:197], off
	v_lshlrev_b32_e32 v168, 16, v82
	v_and_b32_e32 v170, 0xffff0000, v82
	v_lshlrev_b32_e32 v166, 16, v83
	v_and_b32_e32 v164, 0xffff0000, v83
	s_waitcnt vmcnt(7)
	v_mov_b32_e32 v82, v208
	v_mov_b32_e32 v83, v209
	v_add_u32_e32 v208, s2, v225
	v_mad_i64_i32 v[208:209], s[0:1], v208, s93, v[198:199]
	global_load_dwordx2 v[208:209], v[208:209], off offset:32
	v_lshlrev_b32_e32 v169, 16, v82
	v_and_b32_e32 v167, 0xffff0000, v82
	v_lshlrev_b32_e32 v82, 16, v83
	v_and_b32_e32 v83, 0xffff0000, v83
	v_pk_fma_f32 v[82:83], v[82:83], s[30:31], v[68:69] op_sel_hi:[1,0,1]
	v_mov_b32_e32 v171, v169
	v_mul_f32_e32 v68, v82, v82
	v_pk_fma_f32 v[162:163], v[82:83], v[82:83], v[68:69] op_sel_hi:[1,1,0]
	v_mov_b32_e32 v165, v167
	v_mov_b32_e32 v162, v65
	s_waitcnt vmcnt(7)
	v_mov_b32_e32 v68, v210
	v_mov_b32_e32 v69, v211
	v_add_u32_e32 v210, s2, v225
	v_mad_i64_i32 v[210:211], s[0:1], v210, s93, v[198:199]
	global_load_dwordx2 v[210:211], v[210:211], off offset:256
	v_lshlrev_b32_e32 v154, 16, v68
	v_and_b32_e32 v155, 0xffff0000, v68
	v_lshlrev_b32_e32 v68, 16, v69
	v_and_b32_e32 v69, 0xffff0000, v69
	v_pk_fma_f32 v[80:81], v[68:69], s[30:31], v[80:81] op_sel_hi:[1,0,1]
	s_waitcnt vmcnt(7)
	v_mov_b32_e32 v152, v212
	v_mov_b32_e32 v153, v213
	v_add_u32_e32 v212, s2, v225
	v_mad_i64_i32 v[212:213], s[0:1], v212, s93, v[198:199]
	global_load_dwordx2 v[212:213], v[212:213], off offset:288
	v_lshlrev_b32_e32 v68, 16, v152
	v_and_b32_e32 v69, 0xffff0000, v152
	v_pk_fma_f32 v[68:69], v[68:69], s[30:31], v[74:75] op_sel_hi:[1,0,1]
	v_lshlrev_b32_e32 v74, 16, v153
	v_and_b32_e32 v75, 0xffff0000, v153
	v_pk_fma_f32 v[74:75], v[74:75], s[30:31], v[76:77] op_sel_hi:[1,0,1]
	v_mov_b32_e32 v76, v70
	v_mov_b32_e32 v77, v66
	v_pk_mov_b32 v[70:71], v[70:71], v[66:67] op_sel:[1,0]
	v_mov_b32_e32 v66, v72
	v_pk_fma_f32 v[76:77], v[168:169], s[30:31], v[76:77] op_sel_hi:[1,0,1]
	v_pk_fma_f32 v[152:153], v[170:171], s[30:31], v[70:71] op_sel_hi:[1,0,1]
	v_pk_fma_f32 v[70:71], v[166:167], s[30:31], v[66:67] op_sel_hi:[1,0,1]
	v_mov_b32_e32 v66, v73
	v_pk_fma_f32 v[72:73], v[164:165], s[30:31], v[66:67] op_sel_hi:[1,0,1]
	v_pk_mul_f32 v[66:67], v[76:77], v[76:77]
	v_pk_mul_f32 v[164:165], v[152:153], v[152:153]
	v_pk_mul_f32 v[166:167], v[70:71], v[70:71]
	v_pk_mul_f32 v[168:169], v[72:73], v[72:73]
	v_pk_mov_b32 v[66:67], v[76:77], v[66:67] op_sel:[1,0]
	v_pk_mov_b32 v[164:165], v[70:71], v[164:165] op_sel:[1,0]
	v_pk_fma_f32 v[78:79], v[154:155], s[30:31], v[78:79] op_sel_hi:[1,0,1]
	v_pk_add_f32 v[66:67], v[66:67], v[164:165]
	v_mov_b32_e32 v164, v82
	v_mov_b32_e32 v165, v166
	v_pk_mov_b32 v[166:167], v[82:83], v[168:169] op_sel:[1,0]
	v_pk_mul_f32 v[168:169], v[70:71], v[72:73]
	v_pk_add_f32 v[164:165], v[164:165], v[166:167]
	v_pk_mul_f32 v[166:167], v[76:77], v[152:153]
	v_pk_add_f32 v[66:67], v[66:67], v[164:165]
	v_pk_add_f32 v[164:165], v[76:77], v[152:153]
	v_pk_mul_f32 v[160:161], v[78:79], v[78:79]
	v_mov_b32_e32 v165, v167
	v_pk_add_f32 v[166:167], v[70:71], v[72:73]
	v_pk_mul_f32 v[156:157], v[80:81], v[80:81]
	v_mov_b32_e32 v167, v169
	v_pk_add_f32 v[164:165], v[164:165], v[166:167]
	v_pk_mul_f32 v[158:159], v[68:69], v[68:69]
	v_pk_add_f32 v[162:163], v[164:165], v[162:163]
	v_pk_mul_f32 v[154:155], v[74:75], v[74:75]
	v_pk_add_f32 v[66:67], v[66:67], v[162:163]
	v_mov_b32_e32 v162, v78
	v_mov_b32_e32 v163, v160
	v_mov_b32_e32 v160, v79
	v_pk_add_f32 v[160:161], v[162:163], v[160:161]
	v_mov_b32_e32 v162, v80
	v_mov_b32_e32 v163, v156
	v_mov_b32_e32 v156, v81
	v_pk_add_f32 v[156:157], v[162:163], v[156:157]
	s_nop 0
	v_pk_add_f32 v[156:157], v[160:161], v[156:157]
	s_nop 0
	v_pk_add_f32 v[66:67], v[66:67], v[156:157]
	v_mov_b32_e32 v156, v68
	v_mov_b32_e32 v157, v158
	v_mov_b32_e32 v158, v69
	v_pk_add_f32 v[156:157], v[156:157], v[158:159]
	v_mov_b32_e32 v158, v74
	v_mov_b32_e32 v159, v154
	v_mov_b32_e32 v154, v75
	v_pk_add_f32 v[154:155], v[158:159], v[154:155]
	s_nop 0
	v_pk_add_f32 v[154:155], v[156:157], v[154:155]
	s_nop 0
	v_pk_add_f32 v[66:67], v[66:67], v[154:155]
	ds_bpermute_b32 v154, v139, v66
	ds_bpermute_b32 v155, v139, v67
	s_waitcnt lgkmcnt(0)
	v_pk_add_f32 v[66:67], v[66:67], v[154:155]
	ds_bpermute_b32 v154, v64, v66
	ds_bpermute_b32 v155, v64, v67
	s_and_saveexec_b64 s[0:1], s[40:41]
	s_cbranch_execz .LBB0_559
	s_waitcnt lgkmcnt(0)
	v_pk_add_f32 v[66:67], v[66:67], v[154:155]
	ds_write_b64 v233, v[66:67]
;     __device__ __forceinline__ void fused(f32x4 (&acc)[2][2][4][2], const Unit& u, int wr, int wc, int fr, int fq, LAS unsigned char* lds) const {
;     ...
;             for (int m = 0; m < 4; ++m) { const int rl = rl0 + ai * HALF + m * 16; const size_t roff = (size_t)(u.pm * BM + rl) * LDX + col0; float s = 0.f, q = 0.f;
; #pragma unroll
;                 for (int bj = 0; bj < 2; ++bj)
; #pragma unroll
;                     for (int n = 0; n < 2; ++n) { const u32x2 w = *(const u32x2*)(res + roff + bj * HALF + n * 16); f32x4 o = acc[ai][bj][m][n];
;                         o[0] += ALPHA * __uint_as_float(w.x << 16); o[1] += ALPHA * __uint_as_float(w.x & 0xffff0000u); o[2] += ALPHA * __uint_as_float(w.y << 16); o[3] += ALPHA * __uint_as_float(w.y & 0xffff0000u);
;                         acc[ai][bj][m][n] = o; s += (o[0] + o[1]) + (o[2] + o[3]); q += (o[0] * o[0] + o[1] * o[1]) + (o[2] * o[2] + o[3] * o[3]); }
;                 s += __shfl_xor(s, 16); s += __shfl_xor(s, 32); q += __shfl_xor(q, 16); q += __shfl_xor(q, 32);
;                 if (fq == 0) { P[(rl * 4 + wc) * 2] = s; P[(rl * 4 + wc) * 2 + 1] = q; }
;                 asm volatile("" ::: "memory"); }
.LBB0_559:
	s_or_b64 exec, exec, s[0:1]
	s_waitcnt lgkmcnt(1)
	v_add_u32_e32 v154, s2, v224
	v_mov_b64_e32 v[66:67], s[28:29]
	v_mad_i64_i32 v[66:67], s[0:1], v154, s93, v[66:67]
	v_lshl_add_u64 v[156:157], v[134:135], 1, v[66:67]
	s_waitcnt vmcnt(7)
	v_mov_b32_e32 v66, v188
	v_mov_b32_e32 v67, v189
	v_add_u32_e32 v188, s2, v226
	v_mad_i64_i32 v[188:189], s[0:1], v188, s93, v[198:199]
	global_load_dwordx2 v[188:189], v[188:189], off
	v_lshlrev_b32_e32 v172, 16, v66
	v_and_b32_e32 v174, 0xffff0000, v66
	v_lshlrev_b32_e32 v170, 16, v67
	v_and_b32_e32 v168, 0xffff0000, v67
	s_waitcnt vmcnt(7)
	v_mov_b32_e32 v66, v190
	v_mov_b32_e32 v67, v191
	v_add_u32_e32 v190, s2, v226
	v_mad_i64_i32 v[190:191], s[0:1], v190, s93, v[198:199]
	global_load_dwordx2 v[190:191], v[190:191], off offset:32
	v_lshlrev_b32_e32 v173, 16, v66
	v_and_b32_e32 v171, 0xffff0000, v66
	v_lshlrev_b32_e32 v66, 16, v67
	v_and_b32_e32 v67, 0xffff0000, v67
	v_pk_fma_f32 v[66:67], v[66:67], s[30:31], v[50:51] op_sel_hi:[1,0,1]
	v_mov_b32_e32 v175, v173
	v_mul_f32_e32 v50, v66, v66
	v_pk_fma_f32 v[166:167], v[66:67], v[66:67], v[50:51] op_sel_hi:[1,1,0]
	v_mov_b32_e32 v169, v171
	v_mov_b32_e32 v166, v65
	s_waitcnt vmcnt(7)
	v_mov_b32_e32 v50, v192
	v_mov_b32_e32 v51, v193
	v_add_u32_e32 v192, s2, v226
	v_mad_i64_i32 v[192:193], s[0:1], v192, s93, v[198:199]
	global_load_dwordx2 v[192:193], v[192:193], off offset:256
	v_lshlrev_b32_e32 v158, 16, v50
	v_and_b32_e32 v159, 0xffff0000, v50
	v_lshlrev_b32_e32 v50, 16, v51
	v_and_b32_e32 v51, 0xffff0000, v51
	v_pk_fma_f32 v[62:63], v[50:51], s[30:31], v[62:63] op_sel_hi:[1,0,1]
	s_waitcnt vmcnt(7)
	v_mov_b32_e32 v156, v194
	v_mov_b32_e32 v157, v195
	v_add_u32_e32 v194, s2, v226
	v_mad_i64_i32 v[194:195], s[0:1], v194, s93, v[198:199]
	global_load_dwordx2 v[194:195], v[194:195], off offset:288
	v_lshlrev_b32_e32 v50, 16, v156
	v_and_b32_e32 v51, 0xffff0000, v156
	v_pk_fma_f32 v[50:51], v[50:51], s[30:31], v[56:57] op_sel_hi:[1,0,1]
	v_lshlrev_b32_e32 v56, 16, v157
	v_and_b32_e32 v57, 0xffff0000, v157
	v_pk_fma_f32 v[56:57], v[56:57], s[30:31], v[58:59] op_sel_hi:[1,0,1]
	v_mov_b32_e32 v58, v52
	v_mov_b32_e32 v59, v48
	v_pk_mov_b32 v[52:53], v[52:53], v[48:49] op_sel:[1,0]
	v_mov_b32_e32 v48, v54
	v_pk_fma_f32 v[58:59], v[172:173], s[30:31], v[58:59] op_sel_hi:[1,0,1]
	v_pk_fma_f32 v[156:157], v[174:175], s[30:31], v[52:53] op_sel_hi:[1,0,1]
	v_pk_fma_f32 v[52:53], v[170:171], s[30:31], v[48:49] op_sel_hi:[1,0,1]
	v_mov_b32_e32 v48, v55
	v_pk_fma_f32 v[54:55], v[168:169], s[30:31], v[48:49] op_sel_hi:[1,0,1]
	v_pk_mul_f32 v[48:49], v[58:59], v[58:59]
	v_pk_mul_f32 v[168:169], v[156:157], v[156:157]
	v_pk_mul_f32 v[170:171], v[52:53], v[52:53]
	v_pk_mul_f32 v[172:173], v[54:55], v[54:55]
	v_pk_mov_b32 v[48:49], v[58:59], v[48:49] op_sel:[1,0]
	v_pk_mov_b32 v[168:169], v[52:53], v[168:169] op_sel:[1,0]
	v_pk_fma_f32 v[60:61], v[158:159], s[30:31], v[60:61] op_sel_hi:[1,0,1]
	v_pk_add_f32 v[48:49], v[48:49], v[168:169]
	v_mov_b32_e32 v168, v66
	v_mov_b32_e32 v169, v170
	v_pk_mov_b32 v[170:171], v[66:67], v[172:173] op_sel:[1,0]
	v_pk_mul_f32 v[172:173], v[52:53], v[54:55]
	v_pk_add_f32 v[168:169], v[168:169], v[170:171]
	v_pk_mul_f32 v[170:171], v[58:59], v[156:157]
	v_pk_add_f32 v[48:49], v[48:49], v[168:169]
	v_pk_add_f32 v[168:169], v[58:59], v[156:157]
	v_pk_mul_f32 v[164:165], v[60:61], v[60:61]
	v_mov_b32_e32 v169, v171
	v_pk_add_f32 v[170:171], v[52:53], v[54:55]
	v_pk_mul_f32 v[160:161], v[62:63], v[62:63]
	v_mov_b32_e32 v171, v173
	v_pk_add_f32 v[168:169], v[168:169], v[170:171]
	v_pk_mul_f32 v[162:163], v[50:51], v[50:51]
	v_pk_add_f32 v[166:167], v[168:169], v[166:167]
	v_pk_mul_f32 v[158:159], v[56:57], v[56:57]
	v_pk_add_f32 v[48:49], v[48:49], v[166:167]
	v_mov_b32_e32 v166, v60
	v_mov_b32_e32 v167, v164
	v_mov_b32_e32 v164, v61
	v_pk_add_f32 v[164:165], v[166:167], v[164:165]
	v_mov_b32_e32 v166, v62
	v_mov_b32_e32 v167, v160
	v_mov_b32_e32 v160, v63
	v_pk_add_f32 v[160:161], v[166:167], v[160:161]
	s_nop 0
	v_pk_add_f32 v[160:161], v[164:165], v[160:161]
	s_nop 0
	v_pk_add_f32 v[48:49], v[48:49], v[160:161]
	v_mov_b32_e32 v160, v50
	v_mov_b32_e32 v161, v162
	v_mov_b32_e32 v162, v51
	v_pk_add_f32 v[160:161], v[160:161], v[162:163]
	v_mov_b32_e32 v162, v56
	v_mov_b32_e32 v163, v158
	v_mov_b32_e32 v158, v57
	v_pk_add_f32 v[158:159], v[162:163], v[158:159]
	s_nop 0
	v_pk_add_f32 v[158:159], v[160:161], v[158:159]
	s_nop 0
	v_pk_add_f32 v[48:49], v[48:49], v[158:159]
	ds_bpermute_b32 v158, v139, v48
	ds_bpermute_b32 v159, v139, v49
	s_waitcnt lgkmcnt(0)
	v_pk_add_f32 v[48:49], v[48:49], v[158:159]
	ds_bpermute_b32 v158, v64, v48
	ds_bpermute_b32 v159, v64, v49
	s_and_saveexec_b64 s[0:1], s[40:41]
	s_cbranch_execz .LBB0_561
	s_waitcnt lgkmcnt(0)
	v_pk_add_f32 v[48:49], v[48:49], v[158:159]
	ds_write_b64 v234, v[48:49]
;     __device__ __forceinline__ void fused(f32x4 (&acc)[2][2][4][2], const Unit& u, int wr, int wc, int fr, int fq, LAS unsigned char* lds) const {
;     ...
;             for (int m = 0; m < 4; ++m) { const int rl = rl0 + ai * HALF + m * 16; const size_t roff = (size_t)(u.pm * BM + rl) * LDX + col0; float s = 0.f, q = 0.f;
; #pragma unroll
;                 for (int bj = 0; bj < 2; ++bj)
; #pragma unroll
;                     for (int n = 0; n < 2; ++n) { const u32x2 w = *(const u32x2*)(res + roff + bj * HALF + n * 16); f32x4 o = acc[ai][bj][m][n];
;                         o[0] += ALPHA * __uint_as_float(w.x << 16); o[1] += ALPHA * __uint_as_float(w.x & 0xffff0000u); o[2] += ALPHA * __uint_as_float(w.y << 16); o[3] += ALPHA * __uint_as_float(w.y & 0xffff0000u);
;                         acc[ai][bj][m][n] = o; s += (o[0] + o[1]) + (o[2] + o[3]); q += (o[0] * o[0] + o[1] * o[1]) + (o[2] * o[2] + o[3] * o[3]); }
;                 s += __shfl_xor(s, 16); s += __shfl_xor(s, 32); q += __shfl_xor(q, 16); q += __shfl_xor(q, 32);
;                 if (fq == 0) { P[(rl * 4 + wc) * 2] = s; P[(rl * 4 + wc) * 2 + 1] = q; }
;                 asm volatile("" ::: "memory"); }
.LBB0_561:
	s_or_b64 exec, exec, s[0:1]
	s_waitcnt lgkmcnt(1)
	v_add_u32_e32 v158, s2, v225
	v_mov_b64_e32 v[48:49], s[28:29]
	v_mad_i64_i32 v[48:49], s[0:1], v158, s93, v[48:49]
	v_lshl_add_u64 v[160:161], v[134:135], 1, v[48:49]
	s_waitcnt vmcnt(7)
	v_mov_b32_e32 v48, v196
	v_mov_b32_e32 v49, v197
	v_add_u32_e32 v196, s2, v227
	v_mad_i64_i32 v[196:197], s[0:1], v196, s93, v[198:199]
	global_load_dwordx2 v[196:197], v[196:197], off
	v_lshlrev_b32_e32 v176, 16, v48
	v_and_b32_e32 v178, 0xffff0000, v48
	v_lshlrev_b32_e32 v174, 16, v49
	v_and_b32_e32 v172, 0xffff0000, v49
	s_waitcnt vmcnt(7)
	v_mov_b32_e32 v48, v208
	v_mov_b32_e32 v49, v209
	v_add_u32_e32 v208, s2, v227
	v_mad_i64_i32 v[208:209], s[0:1], v208, s93, v[198:199]
	global_load_dwordx2 v[208:209], v[208:209], off offset:32
	v_lshlrev_b32_e32 v177, 16, v48
	v_and_b32_e32 v175, 0xffff0000, v48
	v_lshlrev_b32_e32 v48, 16, v49
	v_and_b32_e32 v49, 0xffff0000, v49
	v_pk_fma_f32 v[48:49], v[48:49], s[30:31], v[34:35] op_sel_hi:[1,0,1]
	v_mov_b32_e32 v179, v177
	v_mul_f32_e32 v34, v48, v48
	v_pk_fma_f32 v[170:171], v[48:49], v[48:49], v[34:35] op_sel_hi:[1,1,0]
	v_mov_b32_e32 v173, v175
	v_mov_b32_e32 v170, v65
	s_waitcnt vmcnt(7)
	v_mov_b32_e32 v34, v210
	v_mov_b32_e32 v35, v211
	v_add_u32_e32 v210, s2, v227
	v_mad_i64_i32 v[210:211], s[0:1], v210, s93, v[198:199]
	global_load_dwordx2 v[210:211], v[210:211], off offset:256
	v_lshlrev_b32_e32 v162, 16, v34
	v_and_b32_e32 v163, 0xffff0000, v34
	v_lshlrev_b32_e32 v34, 16, v35
	v_and_b32_e32 v35, 0xffff0000, v35
	v_pk_fma_f32 v[46:47], v[34:35], s[30:31], v[46:47] op_sel_hi:[1,0,1]
	s_waitcnt vmcnt(7)
	v_mov_b32_e32 v160, v212
	v_mov_b32_e32 v161, v213
	v_add_u32_e32 v212, s2, v227
	v_mad_i64_i32 v[212:213], s[0:1], v212, s93, v[198:199]
	global_load_dwordx2 v[212:213], v[212:213], off offset:288
	v_lshlrev_b32_e32 v34, 16, v160
	v_and_b32_e32 v35, 0xffff0000, v160
	v_pk_fma_f32 v[34:35], v[34:35], s[30:31], v[40:41] op_sel_hi:[1,0,1]
	v_lshlrev_b32_e32 v40, 16, v161
	v_and_b32_e32 v41, 0xffff0000, v161
	v_pk_fma_f32 v[40:41], v[40:41], s[30:31], v[42:43] op_sel_hi:[1,0,1]
	v_mov_b32_e32 v42, v36
	v_mov_b32_e32 v43, v32
	v_pk_mov_b32 v[36:37], v[36:37], v[32:33] op_sel:[1,0]
	v_mov_b32_e32 v32, v38
	v_pk_fma_f32 v[42:43], v[176:177], s[30:31], v[42:43] op_sel_hi:[1,0,1]
	v_pk_fma_f32 v[160:161], v[178:179], s[30:31], v[36:37] op_sel_hi:[1,0,1]
	v_pk_fma_f32 v[36:37], v[174:175], s[30:31], v[32:33] op_sel_hi:[1,0,1]
	v_mov_b32_e32 v32, v39
	v_pk_fma_f32 v[38:39], v[172:173], s[30:31], v[32:33] op_sel_hi:[1,0,1]
	v_pk_mul_f32 v[32:33], v[42:43], v[42:43]
	v_pk_mul_f32 v[172:173], v[160:161], v[160:161]
	v_pk_mul_f32 v[174:175], v[36:37], v[36:37]
	v_pk_mul_f32 v[176:177], v[38:39], v[38:39]
	v_pk_mov_b32 v[32:33], v[42:43], v[32:33] op_sel:[1,0]
	v_pk_mov_b32 v[172:173], v[36:37], v[172:173] op_sel:[1,0]
	v_pk_fma_f32 v[44:45], v[162:163], s[30:31], v[44:45] op_sel_hi:[1,0,1]
	v_pk_add_f32 v[32:33], v[32:33], v[172:173]
	v_mov_b32_e32 v172, v48
	v_mov_b32_e32 v173, v174
	v_pk_mov_b32 v[174:175], v[48:49], v[176:177] op_sel:[1,0]
	v_pk_mul_f32 v[176:177], v[36:37], v[38:39]
	v_pk_add_f32 v[172:173], v[172:173], v[174:175]
	v_pk_mul_f32 v[174:175], v[42:43], v[160:161]
	v_pk_add_f32 v[32:33], v[32:33], v[172:173]
	v_pk_add_f32 v[172:173], v[42:43], v[160:161]
	v_pk_mul_f32 v[168:169], v[44:45], v[44:45]
	v_mov_b32_e32 v173, v175
	v_pk_add_f32 v[174:175], v[36:37], v[38:39]
	v_pk_mul_f32 v[164:165], v[46:47], v[46:47]
	v_mov_b32_e32 v175, v177
	v_pk_add_f32 v[172:173], v[172:173], v[174:175]
	v_pk_mul_f32 v[166:167], v[34:35], v[34:35]
	v_pk_add_f32 v[170:171], v[172:173], v[170:171]
	v_pk_mul_f32 v[162:163], v[40:41], v[40:41]
	v_pk_add_f32 v[32:33], v[32:33], v[170:171]
	v_mov_b32_e32 v170, v44
	v_mov_b32_e32 v171, v168
	v_mov_b32_e32 v168, v45
	v_pk_add_f32 v[168:169], v[170:171], v[168:169]
	v_mov_b32_e32 v170, v46
	v_mov_b32_e32 v171, v164
	v_mov_b32_e32 v164, v47
	v_pk_add_f32 v[164:165], v[170:171], v[164:165]
	s_nop 0
	v_pk_add_f32 v[164:165], v[168:169], v[164:165]
	s_nop 0
	v_pk_add_f32 v[32:33], v[32:33], v[164:165]
	v_mov_b32_e32 v164, v34
	v_mov_b32_e32 v165, v166
	v_mov_b32_e32 v166, v35
	v_pk_add_f32 v[164:165], v[164:165], v[166:167]
	v_mov_b32_e32 v166, v40
	v_mov_b32_e32 v167, v162
	v_mov_b32_e32 v162, v41
	v_pk_add_f32 v[162:163], v[166:167], v[162:163]
	s_nop 0
	v_pk_add_f32 v[162:163], v[164:165], v[162:163]
	s_nop 0
	v_pk_add_f32 v[32:33], v[32:33], v[162:163]
	ds_bpermute_b32 v162, v139, v32
	ds_bpermute_b32 v163, v139, v33
	s_waitcnt lgkmcnt(0)
	v_pk_add_f32 v[32:33], v[32:33], v[162:163]
	ds_bpermute_b32 v162, v64, v32
	ds_bpermute_b32 v163, v64, v33
	s_and_saveexec_b64 s[0:1], s[40:41]
	s_cbranch_execz .LBB0_563
	s_waitcnt lgkmcnt(0)
	v_pk_add_f32 v[32:33], v[32:33], v[162:163]
	ds_write_b64 v235, v[32:33]
;     __device__ __forceinline__ void fused(f32x4 (&acc)[2][2][4][2], const Unit& u, int wr, int wc, int fr, int fq, LAS unsigned char* lds) const {
;     ...
;             for (int m = 0; m < 4; ++m) { const int rl = rl0 + ai * HALF + m * 16; const size_t roff = (size_t)(u.pm * BM + rl) * LDX + col0; float s = 0.f, q = 0.f;
; #pragma unroll
;                 for (int bj = 0; bj < 2; ++bj)
; #pragma unroll
;                     for (int n = 0; n < 2; ++n) { const u32x2 w = *(const u32x2*)(res + roff + bj * HALF + n * 16); f32x4 o = acc[ai][bj][m][n];
;                         o[0] += ALPHA * __uint_as_float(w.x << 16); o[1] += ALPHA * __uint_as_float(w.x & 0xffff0000u); o[2] += ALPHA * __uint_as_float(w.y << 16); o[3] += ALPHA * __uint_as_float(w.y & 0xffff0000u);
;                         acc[ai][bj][m][n] = o; s += (o[0] + o[1]) + (o[2] + o[3]); q += (o[0] * o[0] + o[1] * o[1]) + (o[2] * o[2] + o[3] * o[3]); }
;                 s += __shfl_xor(s, 16); s += __shfl_xor(s, 32); q += __shfl_xor(q, 16); q += __shfl_xor(q, 32);
;                 if (fq == 0) { P[(rl * 4 + wc) * 2] = s; P[(rl * 4 + wc) * 2 + 1] = q; }
;                 asm volatile("" ::: "memory"); }
.LBB0_563:
	s_or_b64 exec, exec, s[0:1]
	v_add_u32_e32 v164, s2, v226
	v_mov_b64_e32 v[32:33], s[28:29]
	v_mad_i64_i32 v[32:33], s[0:1], v164, s93, v[32:33]
	v_lshl_add_u64 v[166:167], v[134:135], 1, v[32:33]
	s_waitcnt vmcnt(7)
	v_mov_b32_e32 v32, v188
	v_mov_b32_e32 v33, v189
	v_lshlrev_b32_e32 v180, 16, v32
	v_and_b32_e32 v182, 0xffff0000, v32
	s_waitcnt lgkmcnt(1)
	v_lshlrev_b32_e32 v162, 16, v33
	v_and_b32_e32 v168, 0xffff0000, v33
	s_waitcnt vmcnt(6)
	v_mov_b32_e32 v32, v190
	v_mov_b32_e32 v33, v191
	v_lshlrev_b32_e32 v181, 16, v32
	s_waitcnt lgkmcnt(0)
	v_and_b32_e32 v163, 0xffff0000, v32
	v_lshlrev_b32_e32 v32, 16, v33
	v_and_b32_e32 v33, 0xffff0000, v33
	v_pk_fma_f32 v[32:33], v[32:33], s[30:31], v[18:19] op_sel_hi:[1,0,1]
	v_mov_b32_e32 v183, v181
	v_mul_f32_e32 v18, v32, v32
	v_pk_fma_f32 v[178:179], v[32:33], v[32:33], v[18:19] op_sel_hi:[1,1,0]
	v_mov_b32_e32 v169, v163
	v_mov_b32_e32 v178, v65
	s_waitcnt vmcnt(5)
	v_mov_b32_e32 v18, v192
	v_mov_b32_e32 v19, v193
	v_lshlrev_b32_e32 v170, 16, v18
	v_and_b32_e32 v171, 0xffff0000, v18
	v_lshlrev_b32_e32 v18, 16, v19
	v_and_b32_e32 v19, 0xffff0000, v19
	v_pk_fma_f32 v[30:31], v[18:19], s[30:31], v[30:31] op_sel_hi:[1,0,1]
	s_waitcnt vmcnt(4)
	v_mov_b32_e32 v166, v194
	v_mov_b32_e32 v167, v195
	v_lshlrev_b32_e32 v18, 16, v166
	v_and_b32_e32 v19, 0xffff0000, v166
	v_pk_fma_f32 v[18:19], v[18:19], s[30:31], v[24:25] op_sel_hi:[1,0,1]
	v_lshlrev_b32_e32 v24, 16, v167
	v_and_b32_e32 v25, 0xffff0000, v167
	v_pk_fma_f32 v[24:25], v[24:25], s[30:31], v[26:27] op_sel_hi:[1,0,1]
	v_mov_b32_e32 v26, v20
	v_mov_b32_e32 v27, v16
	v_pk_mov_b32 v[20:21], v[20:21], v[16:17] op_sel:[1,0]
	v_mov_b32_e32 v16, v22
	v_pk_fma_f32 v[26:27], v[180:181], s[30:31], v[26:27] op_sel_hi:[1,0,1]
	v_pk_fma_f32 v[166:167], v[182:183], s[30:31], v[20:21] op_sel_hi:[1,0,1]
	v_pk_fma_f32 v[162:163], v[162:163], s[30:31], v[16:17] op_sel_hi:[1,0,1]
	v_mov_b32_e32 v16, v23
	v_pk_fma_f32 v[168:169], v[168:169], s[30:31], v[16:17] op_sel_hi:[1,0,1]
	v_pk_mul_f32 v[16:17], v[26:27], v[26:27]
	v_pk_mul_f32 v[20:21], v[166:167], v[166:167]
	v_pk_mul_f32 v[22:23], v[162:163], v[162:163]
	v_pk_mul_f32 v[180:181], v[168:169], v[168:169]
	v_pk_mov_b32 v[16:17], v[26:27], v[16:17] op_sel:[1,0]
	v_pk_mov_b32 v[20:21], v[162:163], v[20:21] op_sel:[1,0]
	v_pk_fma_f32 v[28:29], v[170:171], s[30:31], v[28:29] op_sel_hi:[1,0,1]
	v_pk_add_f32 v[16:17], v[16:17], v[20:21]
	v_mov_b32_e32 v20, v32
	v_mov_b32_e32 v21, v22
	v_pk_mov_b32 v[22:23], v[32:33], v[180:181] op_sel:[1,0]
	v_pk_mul_f32 v[180:181], v[162:163], v[168:169]
	v_pk_add_f32 v[20:21], v[20:21], v[22:23]
	v_pk_mul_f32 v[22:23], v[26:27], v[166:167]
	v_pk_add_f32 v[16:17], v[16:17], v[20:21]
	v_pk_add_f32 v[20:21], v[26:27], v[166:167]
	v_pk_mul_f32 v[176:177], v[28:29], v[28:29]
	v_mov_b32_e32 v21, v23
	v_pk_add_f32 v[22:23], v[162:163], v[168:169]
	v_pk_mul_f32 v[172:173], v[30:31], v[30:31]
	v_mov_b32_e32 v23, v181
	v_pk_add_f32 v[20:21], v[20:21], v[22:23]
	v_mov_b32_e32 v22, v30
	v_pk_add_f32 v[20:21], v[20:21], v[178:179]
	v_mov_b32_e32 v23, v172
	v_pk_add_f32 v[16:17], v[16:17], v[20:21]
	v_mov_b32_e32 v20, v28
	v_mov_b32_e32 v21, v176
	v_mov_b32_e32 v176, v29
	v_mov_b32_e32 v172, v31
	v_pk_add_f32 v[20:21], v[20:21], v[176:177]
	v_pk_add_f32 v[22:23], v[22:23], v[172:173]
	v_pk_mul_f32 v[174:175], v[18:19], v[18:19]
	v_pk_mul_f32 v[170:171], v[24:25], v[24:25]
	v_pk_add_f32 v[20:21], v[20:21], v[22:23]
	v_mov_b32_e32 v22, v24
	v_pk_add_f32 v[16:17], v[16:17], v[20:21]
	v_mov_b32_e32 v20, v18
	v_mov_b32_e32 v21, v174
	v_mov_b32_e32 v174, v19
	v_mov_b32_e32 v23, v170
	v_mov_b32_e32 v170, v25
	v_pk_add_f32 v[20:21], v[20:21], v[174:175]
	v_pk_add_f32 v[22:23], v[22:23], v[170:171]
	s_nop 0
	v_pk_add_f32 v[20:21], v[20:21], v[22:23]
	s_nop 0
	v_pk_add_f32 v[16:17], v[16:17], v[20:21]
	ds_bpermute_b32 v20, v139, v16
	ds_bpermute_b32 v21, v139, v17
	s_waitcnt lgkmcnt(0)
	v_pk_add_f32 v[16:17], v[16:17], v[20:21]
	ds_bpermute_b32 v20, v64, v16
	ds_bpermute_b32 v21, v64, v17
	s_and_saveexec_b64 s[0:1], s[40:41]
	s_cbranch_execz .LBB0_565
	s_waitcnt lgkmcnt(0)
	v_pk_add_f32 v[16:17], v[16:17], v[20:21]
	ds_write_b64 v236, v[16:17]
;     __device__ __forceinline__ void fused(f32x4 (&acc)[2][2][4][2], const Unit& u, int wr, int wc, int fr, int fq, LAS unsigned char* lds) const {
;     ...
;             for (int m = 0; m < 4; ++m) { const int rl = rl0 + ai * HALF + m * 16; const size_t roff = (size_t)(u.pm * BM + rl) * LDX + col0; float s = 0.f, q = 0.f;
; #pragma unroll
;                 for (int bj = 0; bj < 2; ++bj)
; #pragma unroll
;                     for (int n = 0; n < 2; ++n) { const u32x2 w = *(const u32x2*)(res + roff + bj * HALF + n * 16); f32x4 o = acc[ai][bj][m][n];
;                         o[0] += ALPHA * __uint_as_float(w.x << 16); o[1] += ALPHA * __uint_as_float(w.x & 0xffff0000u); o[2] += ALPHA * __uint_as_float(w.y << 16); o[3] += ALPHA * __uint_as_float(w.y & 0xffff0000u);
;                         acc[ai][bj][m][n] = o; s += (o[0] + o[1]) + (o[2] + o[3]); q += (o[0] * o[0] + o[1] * o[1]) + (o[2] * o[2] + o[3] * o[3]); }
;                 s += __shfl_xor(s, 16); s += __shfl_xor(s, 32); q += __shfl_xor(q, 16); q += __shfl_xor(q, 32);
;                 if (fq == 0) { P[(rl * 4 + wc) * 2] = s; P[(rl * 4 + wc) * 2 + 1] = q; }
;                 asm volatile("" ::: "memory"); }
.LBB0_565:
	s_or_b64 exec, exec, s[0:1]
	v_add_u32_e32 v174, s2, v227
	v_mov_b64_e32 v[16:17], s[28:29]
	v_mad_i64_i32 v[16:17], s[0:1], v174, s93, v[16:17]
	v_lshl_add_u64 v[170:171], v[134:135], 1, v[16:17]
	s_waitcnt vmcnt(3)
	v_mov_b32_e32 v16, v196
	v_mov_b32_e32 v17, v197
	v_lshlrev_b32_e32 v180, 16, v16
	v_and_b32_e32 v186, 0xffff0000, v16
	v_lshlrev_b32_e32 v172, 16, v17
	v_and_b32_e32 v182, 0xffff0000, v17
	s_waitcnt vmcnt(2)
	v_mov_b32_e32 v16, v208
	v_mov_b32_e32 v17, v209
	v_lshlrev_b32_e32 v181, 16, v16
	v_and_b32_e32 v173, 0xffff0000, v16
	v_lshlrev_b32_e32 v16, 16, v17
	v_and_b32_e32 v17, 0xffff0000, v17
	v_pk_fma_f32 v[22:23], v[16:17], s[30:31], v[2:3] op_sel_hi:[1,0,1]
	v_mov_b32_e32 v187, v181
	v_mul_f32_e32 v2, v22, v22
	v_pk_fma_f32 v[184:185], v[22:23], v[22:23], v[2:3] op_sel_hi:[1,1,0]
	v_mov_b32_e32 v183, v173
	v_mov_b32_e32 v184, v65
	s_waitcnt vmcnt(1)
	v_mov_b32_e32 v2, v210
	v_mov_b32_e32 v3, v211
	v_lshlrev_b32_e32 v16, 16, v2
	v_and_b32_e32 v17, 0xffff0000, v2
	v_lshlrev_b32_e32 v2, 16, v3
	v_and_b32_e32 v3, 0xffff0000, v3
	s_waitcnt lgkmcnt(0)
	v_pk_fma_f32 v[20:21], v[2:3], s[30:31], v[14:15] op_sel_hi:[1,0,1]
	v_pk_fma_f32 v[16:17], v[16:17], s[30:31], v[12:13] op_sel_hi:[1,0,1]
	v_pk_mul_f32 v[176:177], v[20:21], v[20:21]
	v_pk_mul_f32 v[178:179], v[16:17], v[16:17]
	s_waitcnt vmcnt(0)
	v_mov_b32_e32 v2, v212
	v_mov_b32_e32 v3, v213
	v_lshlrev_b32_e32 v12, 16, v2
	v_and_b32_e32 v13, 0xffff0000, v2
	v_lshlrev_b32_e32 v2, 16, v3
	v_and_b32_e32 v3, 0xffff0000, v3
	v_pk_fma_f32 v[14:15], v[2:3], s[30:31], v[10:11] op_sel_hi:[1,0,1]
	v_mov_b32_e32 v10, v4
	v_mov_b32_e32 v11, v0
	v_pk_mov_b32 v[4:5], v[4:5], v[0:1] op_sel:[1,0]
	v_mov_b32_e32 v0, v6
	v_pk_fma_f32 v[170:171], v[180:181], s[30:31], v[10:11] op_sel_hi:[1,0,1]
	v_pk_fma_f32 v[180:181], v[186:187], s[30:31], v[4:5] op_sel_hi:[1,0,1]
	v_pk_fma_f32 v[172:173], v[172:173], s[30:31], v[0:1] op_sel_hi:[1,0,1]
	v_mov_b32_e32 v0, v7
	v_pk_fma_f32 v[182:183], v[182:183], s[30:31], v[0:1] op_sel_hi:[1,0,1]
	v_pk_mul_f32 v[0:1], v[170:171], v[170:171]
	v_pk_mul_f32 v[4:5], v[180:181], v[180:181]
	v_pk_mul_f32 v[6:7], v[172:173], v[172:173]
	v_pk_mul_f32 v[10:11], v[182:183], v[182:183]
	v_pk_mov_b32 v[0:1], v[170:171], v[0:1] op_sel:[1,0]
	v_pk_mov_b32 v[4:5], v[172:173], v[4:5] op_sel:[1,0]
	v_pk_fma_f32 v[12:13], v[12:13], s[30:31], v[8:9] op_sel_hi:[1,0,1]
	v_pk_add_f32 v[0:1], v[0:1], v[4:5]
	v_mov_b32_e32 v4, v22
	v_mov_b32_e32 v5, v6
	v_pk_mov_b32 v[6:7], v[22:23], v[10:11] op_sel:[1,0]
	v_pk_mul_f32 v[10:11], v[172:173], v[182:183]
	v_pk_add_f32 v[4:5], v[4:5], v[6:7]
	v_pk_mul_f32 v[6:7], v[170:171], v[180:181]
	v_pk_add_f32 v[0:1], v[0:1], v[4:5]
	v_pk_add_f32 v[4:5], v[170:171], v[180:181]
	v_pk_mul_f32 v[8:9], v[12:13], v[12:13]
	v_mov_b32_e32 v5, v7
	v_pk_add_f32 v[6:7], v[172:173], v[182:183]
	v_pk_mul_f32 v[2:3], v[14:15], v[14:15]
	v_mov_b32_e32 v7, v11
	v_pk_add_f32 v[4:5], v[4:5], v[6:7]
	v_mov_b32_e32 v6, v20
	v_pk_add_f32 v[4:5], v[4:5], v[184:185]
	v_mov_b32_e32 v7, v176
	v_pk_add_f32 v[0:1], v[0:1], v[4:5]
	v_mov_b32_e32 v4, v16
	v_mov_b32_e32 v5, v178
	v_mov_b32_e32 v178, v17
	v_mov_b32_e32 v176, v21
	v_pk_add_f32 v[4:5], v[4:5], v[178:179]
	v_pk_add_f32 v[6:7], v[6:7], v[176:177]
	s_nop 0
	v_pk_add_f32 v[4:5], v[4:5], v[6:7]
	v_mov_b32_e32 v6, v14
	v_pk_add_f32 v[0:1], v[0:1], v[4:5]
	v_mov_b32_e32 v4, v12
	v_mov_b32_e32 v5, v8
	v_mov_b32_e32 v8, v13
	v_mov_b32_e32 v7, v2
	v_mov_b32_e32 v2, v15
	v_pk_add_f32 v[4:5], v[4:5], v[8:9]
	v_pk_add_f32 v[2:3], v[6:7], v[2:3]
	s_nop 0
	v_pk_add_f32 v[2:3], v[4:5], v[2:3]
	s_nop 0
	v_pk_add_f32 v[0:1], v[0:1], v[2:3]
	ds_bpermute_b32 v2, v139, v0
	ds_bpermute_b32 v3, v139, v1
	s_waitcnt lgkmcnt(0)
	v_pk_add_f32 v[0:1], v[0:1], v[2:3]
	ds_bpermute_b32 v2, v64, v0
	ds_bpermute_b32 v3, v64, v1
	s_and_saveexec_b64 s[0:1], s[40:41]
	s_cbranch_execz .LBB0_567
	s_waitcnt lgkmcnt(0)
	v_pk_add_f32 v[0:1], v[0:1], v[2:3]
	ds_write_b64 v237, v[0:1]
